# diff-attention loop: K/V global loads issued at the P.V start instead of mid QK
# speedup vs baseline: 1.0081x; 1.0081x over previous
.LBB0_147:
	s_bitcmp1_b32 s1, 0
	s_cselect_b32 s0, 0x8400, 0
	s_add_i32 s0, s0, 0
	v_add_u32_e32 v128, s0, v235
	v_add3_u32 v128, v128, v236, v237
	v_xor_b32_e32 v129, 32, v238
	v_add_u32_e32 v245, v128, v129
	v_xor_b32_e32 v129, 64, v238
	v_add_u32_e32 v244, v128, v129
	v_xor_b32_e32 v129, 0x60, v238
	v_add_u32_e32 v243, v128, v129
	v_xor_b32_e32 v129, 0x80, v238
	v_add_u32_e32 v242, v128, v129
	v_xor_b32_e32 v129, 0xa0, v238
	s_andn2_b32 s8, 1, s1
	v_add_u32_e32 v241, v128, v129
	v_xor_b32_e32 v129, 0xc0, v238
	s_mul_i32 s8, s8, 0x8400
	v_add_u32_e32 v240, v128, v129
	v_xor_b32_e32 v129, 0xe0, v238
	s_add_i32 s8, s8, 0
	v_add_u32_e32 v246, v128, v238
	v_add_u32_e32 v239, v128, v129
	v_add3_u32 v160, s8, v205, v207
	ds_read_b64_tr_b16 v[156:157], v246 offset:17408
	ds_read_b64_tr_b16 v[158:159], v246 offset:18432
	ds_read_b64_tr_b16 v[152:153], v245 offset:17408
	ds_read_b64_tr_b16 v[154:155], v245 offset:18432
	ds_read_b64_tr_b16 v[148:149], v244 offset:17408
	ds_read_b64_tr_b16 v[150:151], v244 offset:18432
	ds_read_b64_tr_b16 v[144:145], v243 offset:17408
	ds_read_b64_tr_b16 v[146:147], v243 offset:18432
	ds_read_b64_tr_b16 v[140:141], v242 offset:17408
	ds_read_b64_tr_b16 v[142:143], v242 offset:18432
	ds_read_b64_tr_b16 v[136:137], v241 offset:17408
	ds_read_b64_tr_b16 v[138:139], v241 offset:18432
	ds_read_b64_tr_b16 v[132:133], v240 offset:17408
	ds_read_b64_tr_b16 v[134:135], v240 offset:18432
	ds_read_b64_tr_b16 v[128:129], v239 offset:17408
	ds_read_b64_tr_b16 v[130:131], v239 offset:18432
	s_waitcnt vmcnt(3)
	ds_write_b128 v160, v[16:19]
	v_add3_u32 v16, s8, v227, v228
	s_waitcnt vmcnt(2)
	ds_write_b128 v16, v[20:23]
	v_add_u32_e32 v16, s8, v209
	v_add3_u32 v16, v16, v211, v229
	s_waitcnt vmcnt(1)
	ds_write_b128 v16, v[24:27] offset:17408
	v_add_u32_e32 v16, s8, v230
	v_add3_u32 v16, v16, v231, v232
	s_waitcnt vmcnt(0)
	ds_write_b128 v16, v[28:31] offset:17408
	v_add3_u32 v247, s0, v192, v233
	ds_read_b128 v[20:23], v247
	ds_read_b128 v[188:191], v247 offset:64
	ds_read_b128 v[24:27], v247 offset:128
	s_waitcnt lgkmcnt(2)
	v_mfma_f32_16x16x32_bf16 v[160:163], v[20:23], v[0:3], v[40:43]
	ds_read_b128 v[28:31], v247 offset:1088
	s_add_i32 s8, s1, 3
	s_add_i32 s0, s1, 2
	s_waitcnt lgkmcnt(2)
	v_mfma_f32_16x16x32_bf16 v[188:191], v[188:191], v[4:7], v[160:163]
	s_min_u32 s8, s8, s83
	s_min_u32 s0, s0, s83
	s_lshl_b32 s8, s8, 6
	ds_read_b128 v[160:163], v247 offset:192
	s_waitcnt lgkmcnt(2)
	v_mfma_f32_16x16x32_bf16 v[168:171], v[24:27], v[8:11], v[44:47]
	ds_read_b128 v[24:27], v247 offset:8704
	s_lshl_b32 s0, s0, 6
	v_add_u32_e32 v16, s8, v204
	s_waitcnt lgkmcnt(1)
	v_mfma_f32_16x16x32_bf16 v[160:163], v[160:163], v[12:15], v[168:171]
	s_nop 2
	ds_read_b128 v[168:171], v247 offset:1152
	v_add_u32_e32 v164, s8, v206
	v_add_u32_e32 v184, s0, v208
	v_mfma_f32_16x16x32_bf16 v[172:175], v[28:31], v[0:3], v[40:43]
	ds_read_b128 v[28:31], v247 offset:8832
	v_ashrrev_i32_e32 v17, 31, v16
	v_ashrrev_i32_e32 v165, 31, v164
	s_waitcnt lgkmcnt(0)
	v_mfma_f32_16x16x32_bf16 v[248:251], v[28:31], v[8:11], v[44:47]
	v_add_u32_e32 v28, s0, v210
	v_ashrrev_i32_e32 v185, 31, v184
	v_ashrrev_i32_e32 v29, 31, v28
	v_lshlrev_b64 v[16:17], 11, v[16:17]
	v_lshlrev_b64 v[20:21], 11, v[164:165]
	v_mfma_f32_16x16x32_bf16 v[180:183], v[24:27], v[0:3], v[40:43]
	v_lshlrev_b64 v[24:25], 11, v[184:185]
	v_lshlrev_b64 v[28:29], 11, v[28:29]
	v_lshl_add_u64 v[16:17], v[212:213], 0, v[16:17]
	v_lshl_add_u64 v[20:21], v[214:215], 0, v[20:21]
	v_lshl_add_u64 v[24:25], v[216:217], 0, v[24:25]
	v_lshl_add_u64 v[28:29], v[218:219], 0, v[28:29]
	ds_read_b128 v[184:187], v247 offset:9920
	ds_read_b128 v[164:167], v247 offset:1216
	s_waitcnt lgkmcnt(1)
	v_mfma_f32_16x16x32_bf16 v[194:197], v[184:187], v[8:11], v[44:47]
	ds_read_b128 v[176:179], v247 offset:9792
	s_add_i32 s8, s1, 1
	v_mfma_f32_16x16x32_bf16 v[184:187], v[168:171], v[4:7], v[172:175]
	ds_read_b128 v[168:171], v247 offset:1280
	s_cmp_ge_u32 s8, s82
	s_waitcnt lgkmcnt(2)
	v_mfma_f32_16x16x32_bf16 v[164:167], v[164:167], v[8:11], v[44:47]
	ds_read_b128 v[172:175], v247 offset:9856
	s_waitcnt lgkmcnt(1)
	v_mfma_f32_16x16x32_bf16 v[168:171], v[168:171], v[12:15], v[164:167]
	s_nop 4
	ds_read_b128 v[164:167], v247 offset:8768
	s_waitcnt lgkmcnt(0)
	v_mfma_f32_16x16x32_bf16 v[180:183], v[164:167], v[4:7], v[180:183]
	ds_read_b128 v[164:167], v247 offset:8896
	v_mfma_f32_16x16x32_bf16 v[176:179], v[176:179], v[0:3], v[40:43]
	v_mfma_f32_16x16x32_bf16 v[172:175], v[172:175], v[4:7], v[176:179]
	s_waitcnt lgkmcnt(0)
	v_mfma_f32_16x16x32_bf16 v[164:167], v[164:167], v[12:15], v[248:251]
	s_nop 4
	ds_read_b128 v[176:179], v247 offset:9984
	s_waitcnt lgkmcnt(0)
	v_mfma_f32_16x16x32_bf16 v[176:179], v[176:179], v[12:15], v[194:197]
	s_cbranch_scc1 .LBB0_153
	s_cmp_lg_u32 s1, 0
	s_cselect_b64 s[0:1], -1, 0
	s_and_b32 s9, s8, 3
	s_cmp_lg_u32 s9, 0
	s_cselect_b64 s[14:15], -1, 0
	s_and_b64 s[0:1], s[0:1], s[14:15]
	s_and_b64 vcc, exec, s[0:1]
	s_cbranch_vccnz .LBB0_153
	v_max_f32_e32 v194, v189, v189
	v_max_f32_e32 v195, v188, v188
	v_max_f32_e32 v194, v195, v194
	v_max3_f32 v194, v194, v190, v191
	v_max3_f32 v194, v194, v184, v185
	v_max3_f32 v194, v194, v186, v187
	v_max3_f32 v194, v194, v180, v181
	v_max3_f32 v194, v194, v182, v183
	v_max3_f32 v194, v194, v172, v173
	v_max3_f32 v194, v194, v174, v175
	v_mov_b32_e32 v195, v194
	s_nop 1
	v_permlane16_swap_b32_e32 v194, v195
	v_max_f32_e32 v195, v195, v195
	v_max_f32_e32 v194, v194, v194
	v_max_f32_e32 v194, v194, v195
	v_mov_b32_e32 v195, v194
	s_nop 1
	v_permlane32_swap_b32_e32 v194, v195
	v_max_f32_e32 v195, v195, v195
	v_max_f32_e32 v194, v194, v194
	v_max_f32_e32 v247, v194, v195
	v_cmp_lt_f32_e32 vcc, s44, v247
	s_cbranch_vccz .LBB0_151
	s_nop 0
	v_cndmask_b32_e32 v247, 0, v247, vcc
	v_exp_f32_e64 v194, -v247
	v_lshlrev_b32_e32 v196, 16, v72
	v_and_b32_e32 v197, 0xffff0000, v72
	v_sub_f32_e32 v191, v191, v247
	v_pk_mul_f32 v[196:197], v[194:195], v[196:197] op_sel_hi:[0,1]
	v_cvt_pk_bf16_f32 v72, v196, v197
	v_lshlrev_b32_e32 v196, 16, v73
	v_and_b32_e32 v197, 0xffff0000, v73
	v_pk_mul_f32 v[196:197], v[194:195], v[196:197] op_sel_hi:[0,1]
	v_cvt_pk_bf16_f32 v73, v196, v197
	v_lshlrev_b32_e32 v196, 16, v74
	v_and_b32_e32 v197, 0xffff0000, v74
	v_pk_mul_f32 v[196:197], v[194:195], v[196:197] op_sel_hi:[0,1]
	v_cvt_pk_bf16_f32 v74, v196, v197
	v_lshlrev_b32_e32 v196, 16, v75
	v_and_b32_e32 v197, 0xffff0000, v75
	v_pk_mul_f32 v[196:197], v[194:195], v[196:197] op_sel_hi:[0,1]
	v_cvt_pk_bf16_f32 v75, v196, v197
	v_lshlrev_b32_e32 v196, 16, v56
	v_and_b32_e32 v197, 0xffff0000, v56
	v_pk_mul_f32 v[196:197], v[194:195], v[196:197] op_sel_hi:[0,1]
	v_cvt_pk_bf16_f32 v56, v196, v197
	v_lshlrev_b32_e32 v196, 16, v57
	v_and_b32_e32 v197, 0xffff0000, v57
	v_pk_mul_f32 v[196:197], v[194:195], v[196:197] op_sel_hi:[0,1]
	v_cvt_pk_bf16_f32 v57, v196, v197
	v_lshlrev_b32_e32 v196, 16, v58
	v_and_b32_e32 v197, 0xffff0000, v58
	v_pk_mul_f32 v[196:197], v[194:195], v[196:197] op_sel_hi:[0,1]
	v_cvt_pk_bf16_f32 v58, v196, v197
	v_lshlrev_b32_e32 v196, 16, v59
	v_and_b32_e32 v197, 0xffff0000, v59
	v_pk_mul_f32 v[110:111], v[110:111], v[194:195] op_sel_hi:[1,0]
	v_pk_mul_f32 v[108:109], v[108:109], v[194:195] op_sel_hi:[1,0]
	v_pk_mul_f32 v[122:123], v[122:123], v[194:195] op_sel_hi:[1,0]
	v_pk_mul_f32 v[120:121], v[120:121], v[194:195] op_sel_hi:[1,0]
	v_pk_mul_f32 v[114:115], v[114:115], v[194:195] op_sel_hi:[1,0]
	v_pk_mul_f32 v[112:113], v[112:113], v[194:195] op_sel_hi:[1,0]
	v_pk_mul_f32 v[98:99], v[98:99], v[194:195] op_sel_hi:[1,0]
	v_pk_mul_f32 v[96:97], v[96:97], v[194:195] op_sel_hi:[1,0]
	v_pk_mul_f32 v[86:87], v[86:87], v[194:195] op_sel_hi:[1,0]
	v_pk_mul_f32 v[84:85], v[84:85], v[194:195] op_sel_hi:[1,0]
	v_pk_mul_f32 v[70:71], v[70:71], v[194:195] op_sel_hi:[1,0]
	v_pk_mul_f32 v[68:69], v[68:69], v[194:195] op_sel_hi:[1,0]
	v_pk_mul_f32 v[62:63], v[62:63], v[194:195] op_sel_hi:[1,0]
	v_pk_mul_f32 v[60:61], v[60:61], v[194:195] op_sel_hi:[1,0]
	v_pk_mul_f32 v[50:51], v[50:51], v[194:195] op_sel_hi:[1,0]
	v_pk_mul_f32 v[48:49], v[48:49], v[194:195] op_sel_hi:[1,0]
	v_pk_mul_f32 v[34:35], v[34:35], v[194:195] op_sel_hi:[1,0]
	v_pk_mul_f32 v[32:33], v[32:33], v[194:195] op_sel_hi:[1,0]
	v_pk_mul_f32 v[194:195], v[194:195], v[196:197] op_sel_hi:[0,1]
	v_sub_f32_e32 v190, v190, v247
	v_sub_f32_e32 v189, v189, v247
	v_sub_f32_e32 v188, v188, v247
	v_sub_f32_e32 v187, v187, v247
	v_sub_f32_e32 v186, v186, v247
	v_sub_f32_e32 v185, v185, v247
	v_sub_f32_e32 v184, v184, v247
	v_sub_f32_e32 v183, v183, v247
	v_sub_f32_e32 v182, v182, v247
	v_sub_f32_e32 v181, v181, v247
	v_sub_f32_e32 v180, v180, v247
	v_sub_f32_e32 v175, v175, v247
	v_sub_f32_e32 v174, v174, v247
	v_sub_f32_e32 v173, v173, v247
	v_sub_f32_e32 v172, v172, v247
	v_cvt_pk_bf16_f32 v59, v194, v195
	v_sub_f32_e32 v43, v43, v247
	v_sub_f32_e32 v42, v42, v247
	v_sub_f32_e32 v41, v41, v247
	v_sub_f32_e32 v40, v40, v247

.LBB0_153:
	global_load_dwordx4 v[16:19], v[16:17], off
	global_load_dwordx4 v[20:23], v[20:21], off
	global_load_dwordx4 v[24:27], v[24:25], off offset:1024
	global_load_dwordx4 v[28:31], v[28:29], off offset:1024
	v_mfma_f32_16x16x32_bf16 v[120:123], v[156:159], v[72:75], v[120:123]
	v_exp_f32_e32 v188, v188
	v_exp_f32_e32 v189, v189
	v_mfma_f32_16x16x32_bf16 v[124:127], v[156:159], v[100:103], v[124:127]
	ds_read_b64_tr_b16 v[156:157], v246 offset:25600
	ds_read_b64_tr_b16 v[158:159], v246 offset:26624
	v_mfma_f32_16x16x32_bf16 v[112:115], v[152:155], v[72:75], v[112:115]
	v_exp_f32_e32 v190, v190
	v_exp_f32_e32 v191, v191
	v_mfma_f32_16x16x32_bf16 v[116:119], v[152:155], v[100:103], v[116:119]
	ds_read_b64_tr_b16 v[152:153], v245 offset:25600
	ds_read_b64_tr_b16 v[154:155], v245 offset:26624
	v_mfma_f32_16x16x32_bf16 v[96:99], v[148:151], v[72:75], v[96:99]
	v_exp_f32_e32 v184, v184
	v_exp_f32_e32 v185, v185
	v_mfma_f32_16x16x32_bf16 v[104:107], v[148:151], v[100:103], v[104:107]
	ds_read_b64_tr_b16 v[148:149], v244 offset:25600
	ds_read_b64_tr_b16 v[150:151], v244 offset:26624
	v_mfma_f32_16x16x32_bf16 v[84:87], v[144:147], v[72:75], v[84:87]
	v_exp_f32_e32 v186, v186
	v_exp_f32_e32 v187, v187
	v_mfma_f32_16x16x32_bf16 v[88:91], v[144:147], v[100:103], v[88:91]
	ds_read_b64_tr_b16 v[144:145], v243 offset:25600
	ds_read_b64_tr_b16 v[146:147], v243 offset:26624
	v_mfma_f32_16x16x32_bf16 v[68:71], v[140:143], v[72:75], v[68:71]
	v_exp_f32_e32 v194, v180
	v_exp_f32_e32 v195, v181
	v_mfma_f32_16x16x32_bf16 v[76:79], v[140:143], v[100:103], v[76:79]
	ds_read_b64_tr_b16 v[140:141], v242 offset:25600
	ds_read_b64_tr_b16 v[142:143], v242 offset:26624
	v_mfma_f32_16x16x32_bf16 v[60:63], v[136:139], v[72:75], v[60:63]
	v_exp_f32_e32 v196, v182
	v_exp_f32_e32 v197, v183
	v_mfma_f32_16x16x32_bf16 v[64:67], v[136:139], v[100:103], v[64:67]
	ds_read_b64_tr_b16 v[136:137], v241 offset:25600
	ds_read_b64_tr_b16 v[138:139], v241 offset:26624
	v_mfma_f32_16x16x32_bf16 v[48:51], v[132:135], v[72:75], v[48:51]
	v_exp_f32_e32 v172, v172
	v_exp_f32_e32 v173, v173
	v_mfma_f32_16x16x32_bf16 v[52:55], v[132:135], v[100:103], v[52:55]
	ds_read_b64_tr_b16 v[132:133], v240 offset:25600
	ds_read_b64_tr_b16 v[134:135], v240 offset:26624
	s_mov_b32 s30, s28
	s_mov_b32 s31, s28
	v_mfma_f32_16x16x32_bf16 v[32:35], v[128:131], v[72:75], v[32:35]
	s_mov_b32 s29, s28
	ds_read_b64_tr_b16 v[180:181], v239 offset:25600
	ds_read_b64_tr_b16 v[182:183], v239 offset:26624
	v_exp_f32_e32 v174, v174
	v_mfma_f32_16x16x32_bf16 v[36:39], v[128:131], v[100:103], v[36:39]
	v_mov_b64_e32 v[130:131], s[30:31]
	v_mov_b64_e32 v[128:129], s[28:29]
	v_exp_f32_e32 v175, v175
	s_nop 0
	v_mfma_f32_16x16x32_bf16 v[108:111], v[128:131], v[72:75], v[108:111]
	v_mfma_f32_16x16x32_bf16 v[92:95], v[128:131], v[100:103], v[92:95]
	s_waitcnt lgkmcnt(14)
	v_mfma_f32_16x16x32_bf16 v[120:123], v[156:159], v[56:59], v[120:123]
	v_exp_f32_e32 v100, v160
	v_exp_f32_e32 v101, v161
	v_cvt_pk_bf16_f32 v72, v188, v189
	v_mfma_f32_16x16x32_bf16 v[124:127], v[156:159], v[80:83], v[124:127]
	v_cvt_pk_bf16_f32 v73, v190, v191
	v_cvt_pk_bf16_f32 v74, v184, v185
	v_cvt_pk_bf16_f32 v75, v186, v187
	s_waitcnt lgkmcnt(12)
	v_mfma_f32_16x16x32_bf16 v[112:115], v[152:155], v[56:59], v[112:115]
	v_exp_f32_e32 v102, v162
	v_exp_f32_e32 v103, v163
	v_mfma_f32_16x16x32_bf16 v[116:119], v[152:155], v[80:83], v[116:119]
	s_waitcnt lgkmcnt(10)
	v_mfma_f32_16x16x32_bf16 v[96:99], v[148:151], v[56:59], v[96:99]
	v_exp_f32_e32 v152, v168
	v_exp_f32_e32 v153, v169
	v_mfma_f32_16x16x32_bf16 v[104:107], v[148:151], v[80:83], v[104:107]
	s_waitcnt lgkmcnt(8)
	v_mfma_f32_16x16x32_bf16 v[84:87], v[144:147], v[56:59], v[84:87]
	v_exp_f32_e32 v148, v170
	v_exp_f32_e32 v149, v171
	v_mfma_f32_16x16x32_bf16 v[88:91], v[144:147], v[80:83], v[88:91]
	s_waitcnt lgkmcnt(6)
	v_mfma_f32_16x16x32_bf16 v[68:71], v[140:143], v[56:59], v[68:71]
	v_cvt_pk_bf16_f32 v100, v100, v101
	v_cvt_pk_bf16_f32 v101, v102, v103
	v_cvt_pk_bf16_f32 v102, v152, v153
	v_mfma_f32_16x16x32_bf16 v[76:79], v[140:143], v[80:83], v[76:79]
	v_cvt_pk_bf16_f32 v103, v148, v149
	v_exp_f32_e32 v140, v164
	v_exp_f32_e32 v141, v165
	s_waitcnt lgkmcnt(4)
	v_mfma_f32_16x16x32_bf16 v[60:63], v[136:139], v[56:59], v[60:63]
	v_exp_f32_e32 v142, v166
	v_exp_f32_e32 v143, v167
	v_mfma_f32_16x16x32_bf16 v[64:67], v[136:139], v[80:83], v[64:67]
	s_waitcnt lgkmcnt(2)
	v_mfma_f32_16x16x32_bf16 v[48:51], v[132:135], v[56:59], v[48:51]
	v_exp_f32_e32 v136, v176
	v_exp_f32_e32 v137, v177
	v_mfma_f32_16x16x32_bf16 v[52:55], v[132:135], v[80:83], v[52:55]
	s_waitcnt lgkmcnt(0)
	v_mfma_f32_16x16x32_bf16 v[32:35], v[180:183], v[56:59], v[32:35]
	v_exp_f32_e32 v132, v178
	v_exp_f32_e32 v133, v179
	v_mfma_f32_16x16x32_bf16 v[36:39], v[180:183], v[80:83], v[36:39]
	v_mfma_f32_16x16x32_bf16 v[108:111], v[128:131], v[56:59], v[108:111]
	v_mfma_f32_16x16x32_bf16 v[92:95], v[128:131], v[80:83], v[92:95]
	s_waitcnt lgkmcnt(0)
	s_barrier
	v_cvt_pk_bf16_f32 v56, v194, v195
	v_cvt_pk_bf16_f32 v57, v196, v197
	v_cvt_pk_bf16_f32 v58, v172, v173
	v_cvt_pk_bf16_f32 v59, v174, v175
	v_cvt_pk_bf16_f32 v80, v140, v141
	v_cvt_pk_bf16_f32 v81, v142, v143
	v_cvt_pk_bf16_f32 v82, v136, v137
	v_cvt_pk_bf16_f32 v83, v132, v133
	s_cmp_lg_u32 s82, s8
	s_cbranch_scc0 .LBB0_139
	s_mov_b32 s1, s8
	s_branch .LBB0_147
